# phase-0 cache-conversion loop fully unrolled: all 16 loads of a thread's four elements issued before the first convert/store (prologue de-serialisation)
# baseline (speedup 1.0000x reference)
.LBB0_8:
	v_lshl_add_u64 v[12:13], s[20:21], 0, v[2:3]
	v_bfe_u32 v11, v10, 2, 2
	v_lshl_add_u64 v[14:15], s[24:25], 0, v[2:3]
	global_load_dword v66, v[12:13], off
	global_load_dword v67, v[14:15], off
	v_lshlrev_b32_e32 v12, 2, v11
	v_cmp_ne_u32_e32 vcc, 2, v11
	v_ashrrev_i32_e32 v16, 6, v10
	v_ashrrev_i32_e32 v17, 7, v10
	v_cndmask_b32_e32 v12, 4, v12, vcc
	v_cmp_ne_u32_e32 vcc, 1, v11
	v_ashrrev_i32_e32 v6, 8, v10
	v_lshlrev_b32_e32 v20, 2, v6
	v_cndmask_b32_e32 v11, 8, v12, vcc
	v_and_or_b32 v11, v10, s8, v11
	v_and_or_b32 v12, v16, s9, v11
	v_and_or_b32 v14, v17, s9, v11
	v_ashrrev_i32_e32 v13, 31, v12
	v_ashrrev_i32_e32 v15, 31, v14
	v_lshlrev_b64 v[12:13], 8, v[12:13]
	v_and_b32_e32 v6, 0xfc, v20
	v_lshlrev_b64 v[14:15], 9, v[14:15]
	v_lshl_add_u64 v[12:13], s[22:23], 0, v[12:13]
	v_lshl_add_u64 v[14:15], s[26:27], 0, v[14:15]
	v_lshl_add_u64 v[12:13], v[12:13], 0, v[6:7]
	v_and_b32_e32 v6, 0x1fc, v20
	global_load_dword v68, v[12:13], off
	v_lshl_add_u64 v[12:13], v[14:15], 0, v[6:7]
	global_load_dword v69, v[12:13], off
	v_add_u32_e32 v10, s12, v10
	v_lshl_add_u64 v[2:3], v[2:3], 0, s[2:3]
	v_lshl_add_u64 v[12:13], s[20:21], 0, v[2:3]
	v_bfe_u32 v11, v10, 2, 2
	v_lshl_add_u64 v[14:15], s[24:25], 0, v[2:3]
	global_load_dword v70, v[12:13], off
	global_load_dword v71, v[14:15], off
	v_lshlrev_b32_e32 v12, 2, v11
	v_cmp_ne_u32_e32 vcc, 2, v11
	v_ashrrev_i32_e32 v16, 6, v10
	v_ashrrev_i32_e32 v17, 7, v10
	v_cndmask_b32_e32 v12, 4, v12, vcc
	v_cmp_ne_u32_e32 vcc, 1, v11
	v_ashrrev_i32_e32 v6, 8, v10
	v_lshlrev_b32_e32 v20, 2, v6
	v_cndmask_b32_e32 v11, 8, v12, vcc
	v_and_or_b32 v11, v10, s8, v11
	v_and_or_b32 v12, v16, s9, v11
	v_and_or_b32 v14, v17, s9, v11
	v_ashrrev_i32_e32 v13, 31, v12
	v_ashrrev_i32_e32 v15, 31, v14
	v_lshlrev_b64 v[12:13], 8, v[12:13]
	v_and_b32_e32 v6, 0xfc, v20
	v_lshlrev_b64 v[14:15], 9, v[14:15]
	v_lshl_add_u64 v[12:13], s[22:23], 0, v[12:13]
	v_lshl_add_u64 v[14:15], s[26:27], 0, v[14:15]
	v_lshl_add_u64 v[12:13], v[12:13], 0, v[6:7]
	v_and_b32_e32 v6, 0x1fc, v20
	global_load_dword v72, v[12:13], off
	v_lshl_add_u64 v[12:13], v[14:15], 0, v[6:7]
	global_load_dword v73, v[12:13], off
	v_add_u32_e32 v10, s12, v10
	v_lshl_add_u64 v[2:3], v[2:3], 0, s[2:3]
	v_lshl_add_u64 v[12:13], s[20:21], 0, v[2:3]
	v_bfe_u32 v11, v10, 2, 2
	v_lshl_add_u64 v[14:15], s[24:25], 0, v[2:3]
	global_load_dword v74, v[12:13], off
	global_load_dword v75, v[14:15], off
	v_lshlrev_b32_e32 v12, 2, v11
	v_cmp_ne_u32_e32 vcc, 2, v11
	v_ashrrev_i32_e32 v16, 6, v10
	v_ashrrev_i32_e32 v17, 7, v10
	v_cndmask_b32_e32 v12, 4, v12, vcc
	v_cmp_ne_u32_e32 vcc, 1, v11
	v_ashrrev_i32_e32 v6, 8, v10
	v_lshlrev_b32_e32 v20, 2, v6
	v_cndmask_b32_e32 v11, 8, v12, vcc
	v_and_or_b32 v11, v10, s8, v11
	v_and_or_b32 v12, v16, s9, v11
	v_and_or_b32 v14, v17, s9, v11
	v_ashrrev_i32_e32 v13, 31, v12
	v_ashrrev_i32_e32 v15, 31, v14
	v_lshlrev_b64 v[12:13], 8, v[12:13]
	v_and_b32_e32 v6, 0xfc, v20
	v_lshlrev_b64 v[14:15], 9, v[14:15]
	v_lshl_add_u64 v[12:13], s[22:23], 0, v[12:13]
	v_lshl_add_u64 v[14:15], s[26:27], 0, v[14:15]
	v_lshl_add_u64 v[12:13], v[12:13], 0, v[6:7]
	v_and_b32_e32 v6, 0x1fc, v20
	global_load_dword v76, v[12:13], off
	v_lshl_add_u64 v[12:13], v[14:15], 0, v[6:7]
	global_load_dword v77, v[12:13], off
	v_add_u32_e32 v10, s12, v10
	v_lshl_add_u64 v[2:3], v[2:3], 0, s[2:3]
	v_lshl_add_u64 v[12:13], s[20:21], 0, v[2:3]
	v_bfe_u32 v11, v10, 2, 2
	v_lshl_add_u64 v[14:15], s[24:25], 0, v[2:3]
	global_load_dword v78, v[12:13], off
	global_load_dword v79, v[14:15], off
	v_lshlrev_b32_e32 v12, 2, v11
	v_cmp_ne_u32_e32 vcc, 2, v11
	v_ashrrev_i32_e32 v16, 6, v10
	v_ashrrev_i32_e32 v17, 7, v10
	v_cndmask_b32_e32 v12, 4, v12, vcc
	v_cmp_ne_u32_e32 vcc, 1, v11
	v_ashrrev_i32_e32 v6, 8, v10
	v_lshlrev_b32_e32 v20, 2, v6
	v_cndmask_b32_e32 v11, 8, v12, vcc
	v_and_or_b32 v11, v10, s8, v11
	v_and_or_b32 v12, v16, s9, v11
	v_and_or_b32 v14, v17, s9, v11
	v_ashrrev_i32_e32 v13, 31, v12
	v_ashrrev_i32_e32 v15, 31, v14
	v_lshlrev_b64 v[12:13], 8, v[12:13]
	v_and_b32_e32 v6, 0xfc, v20
	v_lshlrev_b64 v[14:15], 9, v[14:15]
	v_lshl_add_u64 v[12:13], s[22:23], 0, v[12:13]
	v_lshl_add_u64 v[14:15], s[26:27], 0, v[14:15]
	v_lshl_add_u64 v[12:13], v[12:13], 0, v[6:7]
	v_and_b32_e32 v6, 0x1fc, v20
	global_load_dword v80, v[12:13], off
	v_lshl_add_u64 v[12:13], v[14:15], 0, v[6:7]
	global_load_dword v81, v[12:13], off
	v_add_u32_e32 v10, s12, v10
	v_lshl_add_u64 v[2:3], v[2:3], 0, s[2:3]
	v_add_co_u32_e32 v12, vcc, 0x200000, v4
	s_nop 1
	v_addc_co_u32_e32 v13, vcc, 0, v5, vcc
	v_add_co_u32_e32 v14, vcc, s10, v4
	s_nop 1
	v_addc_co_u32_e32 v15, vcc, 0, v5, vcc
	v_add_co_u32_e32 v16, vcc, 0x300000, v4
	s_nop 1
	v_addc_co_u32_e32 v17, vcc, 0, v5, vcc
	s_waitcnt vmcnt(12)
	v_cvt_pk_bf16_f32 v66, v66, s0
	v_cvt_pk_bf16_f32 v67, v67, s0
	v_cvt_pk_bf16_f32 v68, v68, s0
	v_cvt_pk_bf16_f32 v69, v69, s0
	global_store_short v[4:5], v66, off
	global_store_short v[12:13], v67, off
	global_store_short v[14:15], v68, off
	global_store_short v[16:17], v69, off
	v_lshl_add_u64 v[4:5], v[4:5], 0, s[4:5]
	v_add_co_u32_e32 v12, vcc, 0x200000, v4
	s_nop 1
	v_addc_co_u32_e32 v13, vcc, 0, v5, vcc
	v_add_co_u32_e32 v14, vcc, s10, v4
	s_nop 1
	v_addc_co_u32_e32 v15, vcc, 0, v5, vcc
	v_add_co_u32_e32 v16, vcc, 0x300000, v4
	s_nop 1
	v_addc_co_u32_e32 v17, vcc, 0, v5, vcc
	s_waitcnt vmcnt(12)
	v_cvt_pk_bf16_f32 v70, v70, s0
	v_cvt_pk_bf16_f32 v71, v71, s0
	v_cvt_pk_bf16_f32 v72, v72, s0
	v_cvt_pk_bf16_f32 v73, v73, s0
	global_store_short v[4:5], v70, off
	global_store_short v[12:13], v71, off
	global_store_short v[14:15], v72, off
	global_store_short v[16:17], v73, off
	v_lshl_add_u64 v[4:5], v[4:5], 0, s[4:5]
	v_add_co_u32_e32 v12, vcc, 0x200000, v4
	s_nop 1
	v_addc_co_u32_e32 v13, vcc, 0, v5, vcc
	v_add_co_u32_e32 v14, vcc, s10, v4
	s_nop 1
	v_addc_co_u32_e32 v15, vcc, 0, v5, vcc
	v_add_co_u32_e32 v16, vcc, 0x300000, v4
	s_nop 1
	v_addc_co_u32_e32 v17, vcc, 0, v5, vcc
	s_waitcnt vmcnt(12)
	v_cvt_pk_bf16_f32 v74, v74, s0
	v_cvt_pk_bf16_f32 v75, v75, s0
	v_cvt_pk_bf16_f32 v76, v76, s0
	v_cvt_pk_bf16_f32 v77, v77, s0
	global_store_short v[4:5], v74, off
	global_store_short v[12:13], v75, off
	global_store_short v[14:15], v76, off
	global_store_short v[16:17], v77, off
	v_lshl_add_u64 v[4:5], v[4:5], 0, s[4:5]
	v_add_co_u32_e32 v12, vcc, 0x200000, v4
	s_nop 1
	v_addc_co_u32_e32 v13, vcc, 0, v5, vcc
	v_add_co_u32_e32 v14, vcc, s10, v4
	s_nop 1
	v_addc_co_u32_e32 v15, vcc, 0, v5, vcc
	v_add_co_u32_e32 v16, vcc, 0x300000, v4
	s_nop 1
	v_addc_co_u32_e32 v17, vcc, 0, v5, vcc
	s_waitcnt vmcnt(12)
	v_cvt_pk_bf16_f32 v78, v78, s0
	v_cvt_pk_bf16_f32 v79, v79, s0
	v_cvt_pk_bf16_f32 v80, v80, s0
	v_cvt_pk_bf16_f32 v81, v81, s0
	global_store_short v[4:5], v78, off
	global_store_short v[12:13], v79, off
	global_store_short v[14:15], v80, off
	global_store_short v[16:17], v81, off
	v_lshl_add_u64 v[4:5], v[4:5], 0, s[4:5]
